# sample attention queue: one atomic claims two consecutive units (no atomic, no store drain before the second unit); on top of page-table prefetch and barrier leader wait removal
# baseline (speedup 1.0000x reference)
.LBB0_1582:
	v_readlane_b32 s0, v255, 12
	v_readlane_b32 s1, v255, 13
	s_cmp_lt_i32 s0, 7
	s_cselect_b64 s[0:1], -1, 0
	s_and_b64 s[18:19], s[0:1], s[2:3]
	s_andn2_b64 vcc, exec, s[18:19]
	s_cbranch_vccnz .LBB0_2069
	s_and_b32 s37, s87, 0xffffffc0
	s_waitcnt vmcnt(0)
	v_mbcnt_lo_u32_b32 v0, -1, 0
	v_mbcnt_hi_u32_b32 v0, -1, v0
	s_mov_b32 s22, 0
	v_add_u32_e32 v0, s37, v0
	s_ashr_i32 s23, s22, 31
	v_readlane_b32 s0, v255, 4
	v_readlane_b32 s1, v255, 5
	s_add_u32 s20, s0, s22
	s_addc_u32 s21, s1, s23
	s_sub_i32 s0, s73, 0x84
	s_cmp_lt_i32 s33, s0
	v_readlane_b32 s0, v255, 9
	v_readlane_b32 s1, v255, 10
	s_mov_b32 s1, 0
	v_writelane_b32 v255, s0, 9
	s_nop 1
	v_writelane_b32 v255, s1, 10
	s_cbranch_scc1 .LBB0_1624
	v_mbcnt_lo_u32_b32 v0, -1, 0
	v_mbcnt_hi_u32_b32 v0, -1, v0
	v_readlane_b32 s0, v255, 14
	v_add_u32_e32 v0, s37, v0
	s_cmp_lt_u32 s0, 64
	v_readlane_b32 s30, v255, 9
	s_cselect_b64 s[0:1], -1, 0
	s_add_i32 s2, s30, 1
	v_and_b32_e32 v176, 63, v0
	v_cvt_f32_u32_e32 v0, s2
	s_mov_b32 s3, 0x42fc0000
	v_mov_b32_e32 v1, 0x42800000
	s_lshl_b32 s2, s30, 14
	v_cmp_lt_f32_e32 vcc, s3, v0
	s_add_i32 s39, s2, 0
	s_and_b64 s[2:3], vcc, exec
	v_cndmask_b32_e32 v1, 0, v1, vcc
	v_sub_f32_e32 v0, v1, v0
	v_exp_f32_e32 v0, v0
	s_cselect_b32 s2, 0xffffffc0, 0
	v_readlane_b32 s31, v255, 10
	v_readlane_b32 s6, v255, 2
	v_ldexp_f32 v0, v0, s2
	s_lshl_b32 s2, s30, 8
	s_add_u32 s4, s20, s2
	s_addc_u32 s5, s21, 0
	s_add_u32 s8, s4, 0x47000000
	s_addc_u32 s9, s5, 0
	s_lshl_b64 s[10:11], s[30:31], 7
	s_lshl_b64 s[2:3], s[22:23], 3
	v_readlane_b32 s7, v255, 3
	s_add_u32 s12, s6, s2
	s_addc_u32 s13, s7, s3
	s_add_u32 s14, s20, 0x61800000
	s_addc_u32 s15, s21, 0
	s_add_u32 s16, s20, 0x61900000
	s_addc_u32 s17, s21, 0
	s_add_u32 s24, s20, 0x61a00000
	s_addc_u32 s25, s21, 0
	s_add_u32 s26, s4, 0x48100000
	s_addc_u32 s27, s5, 0
	s_add_u32 s28, s4, 0x49200000
	v_mul_f32_e32 v177, 0x3fb8aa3b, v0
	s_addc_u32 s29, s5, 0
	v_cndmask_b32_e64 v0, 0, 1, s[0:1]
	s_add_i32 s46, 0, 0x23f40
	s_movk_i32 s44, 0x2000
	s_add_i32 s45, s39, 0x2000
	s_lshl_b64 s[30:31], s[30:31], 9
	v_cmp_ne_u32_e64 s[2:3], 1, v0
	v_mov_b32_e32 v137, 0
	v_mov_b32_e32 v178, s46
	s_movk_i32 s47, 0x110
	s_movk_i32 s49, 0x4000
	s_movk_i32 s56, 0x6000
	s_mov_b32 s57, 0x8000
	s_mov_b32 s58, 0xa000
	s_mov_b32 s59, 0xc000
	s_mov_b32 s60, 0xe000
	s_mov_b32 s61, 0x10000
	s_mov_b32 s62, 0x12000
	s_mov_b32 s63, 0x14000
	s_mov_b32 s64, 0x16000
	s_mov_b32 s65, 0x18000
	s_mov_b32 s66, 0x1a000
	s_mov_b32 s67, 0x1c000
	s_mov_b32 s68, 0x1e000
	s_mov_b32 s69, 0x64000
	s_mov_b32 s70, 0x66000
	s_mov_b32 s71, 0x68000
	s_mov_b32 s72, 0x6a000
	s_mov_b32 s74, 0x6c000
	s_mov_b32 s76, 0x6e000
	s_mov_b32 s77, 0x70000
	s_mov_b32 s78, 0x72000
	s_mov_b32 s79, 0x74000
	s_mov_b32 s80, 0x76000
	s_mov_b32 s81, 0x78000
	s_mov_b32 s82, 0x7a000
	s_mov_b32 s83, 0x7c000
	s_mov_b32 s84, 0x7e000
	s_movk_i32 s85, 0x210
	s_movk_i32 s86, 0x1000
	s_mov_b32 s87, 0x61a00000
	v_mov_b32_e32 v179, 0xf149f2ca
	s_mov_b32 s96, 0
	s_branch .LBB0_1588

.LBB0_1588:
	s_and_b64 vcc, exec, s[2:3]
	s_waitcnt lgkmcnt(0)
	s_barrier
	s_cbranch_vccnz .LBB0_1594
	v_mbcnt_lo_u32_b32 v0, -1, 0
	v_mbcnt_hi_u32_b32 v0, -1, v0
	s_nop 0
	v_cmp_eq_u32_e32 vcc, 0, v0
	s_and_saveexec_b64 s[4:5], vcc
	s_cbranch_execz .LBB0_1593
	s_mov_b64 s[34:35], exec
	v_mbcnt_lo_u32_b32 v0, s34, 0
	v_mbcnt_hi_u32_b32 v0, s35, v0
	v_cmp_eq_u32_e32 vcc, 0, v0
	s_and_saveexec_b64 s[6:7], vcc
	s_cbranch_execz .LBB0_1592
	s_cmp_eq_u32 s96, 0
	s_cbranch_scc0 .Lclaim_have
	s_bcnt1_i32_b64 s0, s[34:35]
	s_lshl_b32 s0, s0, 1
	v_mov_b32_e32 v1, s0
	v_readlane_b32 s0, v255, 4
	v_readlane_b32 s1, v255, 5
	s_nop 4
	global_atomic_add v1, v137, v1, s[0:1] offset:256 sc0
	s_waitcnt vmcnt(0)
	v_readfirstlane_b32 s0, v1
	s_add_i32 s96, s0, 2
	s_branch .Lclaim_done
.Lclaim_have:
	s_add_i32 s0, s96, -1
	s_mov_b32 s96, 0
.Lclaim_done:
.LBB0_1592:
	s_or_b64 exec, exec, s[6:7]
	v_mov_b32_e32 v1, s46
	s_nop 0
	v_add_u32_e32 v0, s0, v0
	ds_write_b32 v1, v0
